# phase-3 attention units run at s_setprio 3 (reset to 0 after the unit)
# speedup vs baseline: 1.0034x; 1.0034x over previous
; DI void attn_unit(const Params& p, int l, int unit, unsigned char* smem) {
;     ...
;   int b, hd, q0, nkeys;
;   if (unit < 512) { b = unit >> 7; hd = (unit >> 5) & 3; q0 = CTX + (unit & 31) * 128; nkeys = SP; }
;   else { const int u = unit - 512; b = u >> 3; hd = (u >> 1) & 3; q0 = (u & 1) * 128; nkeys = CTX; }
; __global__ void __launch_bounds__(256, 2) mega(Params p) {
;     ...
;         const int it = s_item - n_att3 + dft0;
;         if (it >= N_DFT + N_DN + N_HG) break;
;         if (it < dft0) attn_unit(p, l, 448 + (it - dft0) + n_att3, smem);
.LBB0_471:
	s_setprio 3
	s_andn2_b64 vcc, exec, s[4:5]
	s_cbranch_vccnz .LBB0_309
	s_add_i32 s24, s38, 0x1c0
	s_mov_b64 s[4:5], s[84:85]
	v_mov_b32_e32 v144, v216
	s_cmpk_gt_i32 s24, 0x1ff
	s_mov_b64 s[6:7], -1
	s_cbranch_scc0 .LBB0_474
	s_sub_i32 s6, s38, 64
	s_lshr_b32 s26, s6, 3
	s_lshl_b32 s6, s38, 7
	s_lshr_b32 s8, s24, 1
	s_and_b32 s44, s6, 0x80
	s_mov_b64 s[6:7], 0

; __global__ void __launch_bounds__(256, 2) mega(Params p) {
;     ...
;         if (it < dft0) attn_unit(p, l, 448 + (it - dft0) + n_att3, smem);
;         else if (it < N_DFT) dft_tile(p, it, smem);
;         else if (it < N_DFT + N_DN) dn_prep_unit(p, l, it - N_DFT, smem);
;         else hg_prep_unit(p, l, it - N_DFT - N_DN, smem);
;       }
.LBB0_481:
	s_setprio 0
	s_cbranch_execz .LBB0_463
	s_branch .LBB0_470
